# P1 K-rope epilogue: rope-table rows of the next row group requested one group ahead into a second register set (waits no longer drain the group's stores)
# baseline (speedup 1.0000x reference)
;     template <int MODE>
;     DI void rows(const pg8::f32x4 (&acc)[2][2][4][2], const pg8::Unit& u, int wr, int wc, int fr, int fq) const {
;     ...
;                 const int row = u.pm * 256 + ai * 128 + wr * 64 + m * 16 + fr;
;                 v2f cs[8];
;                 if constexpr (MODE <= 1) {
;                     const int pos = row < MP ? (row & (SEQ - 1)) : PAST + ((row - MP) & (DS - 1));
;                     const v4f* rp = (const v4f*)(rope + (size_t)pos * 8);
; #pragma unroll
;                     for (int i = 0; i < 4; ++i) { const v4f t = rp[i]; cs[2 * i] = (v2f){t.x, t.y}; cs[2 * i + 1] = (v2f){t.z, t.w}; }
;                 }
; #pragma unroll
;                 for (int bj = 0; bj < 2; ++bj) {
;                     float v[8];
; #pragma unroll
;                     for (int i = 0; i < 4; ++i) { v[i] = acc[ai][bj][m][0][i]; v[4 + i] = acc[ai][bj][m][1][i]; }
;                     const int col = pn * 256 + bj * 128 + tc0;
;                     if constexpr (MODE <= 1) {
;                         if ((wc & 1) == 0) {
;                             const float sgn = fq == 0 ? -1.f : 1.f;
; #pragma unroll
;                             for (int i = 0; i < 8; ++i) { const float pr = __shfl_xor(v[i], 16); const float r = v[i] * cs[i].x + sgn * pr * cs[i].y; v[i] = fq < 2 ? r : v[i]; }
;                         }
.LBB0_393:
	s_andn2_b64 vcc, exec, s[2:3]
	s_cbranch_vccnz .LBB0_558
	s_cmp_gt_i32 s8, 0
	s_mov_b64 s[2:3], -1
	s_cbranch_scc0 .LBB0_524
	s_lshl_b32 s79, s52, 8
	s_add_i32 s45, s79, s66
	v_or_b32_e32 v180, s45, v1
	v_bitop3_b32 v130, s45, v215, v1 bitop3:0xc8
	v_cmp_gt_i32_e64 s[8:9], s67, v180
	v_cmp_lt_i32_e64 s[6:7], s75, v180
	s_andn2_b64 vcc, exec, s[30:31]
	v_cndmask_b32_e64 v130, v200, v130, s[8:9]
	v_lshlrev_b32_e32 v130, 6, v130
	global_load_dwordx4 v[138:141], v130, s[20:21] offset:48
	global_load_dwordx4 v[142:145], v130, s[20:21] offset:32
	global_load_dwordx4 v[146:149], v130, s[20:21] offset:16
	global_load_dwordx4 v[150:153], v130, s[20:21]
	v_or_b32_e32 v245, 16, v180
	v_bitop3_b32 v244, v180, s94, 16 bitop3:0xc8
	v_cmp_gt_i32_e64 s[98:99], s67, v245
	v_cndmask_b32_e64 v244, v200, v244, s[98:99]
	v_lshlrev_b32_e32 v244, 6, v244
	global_load_dwordx4 v[228:231], v244, s[20:21] offset:48
	global_load_dwordx4 v[232:235], v244, s[20:21] offset:32
	global_load_dwordx4 v[236:239], v244, s[20:21] offset:16
	global_load_dwordx4 v[240:243], v244, s[20:21]
	v_cndmask_b32_e64 v130, 0, 1, s[30:31]
	v_cmp_ne_u32_e64 s[4:5], 1, v130
	s_cbranch_vccnz .LBB0_397
	v_mov_b64_e32 v[136:137], v[128:129]
	s_mov_b64 s[2:3], 0
	v_mov_b32_e32 v179, v129
	v_mov_b32_e32 v178, v128
	v_mov_b32_e32 v219, v127
	v_mov_b32_e32 v181, v126
	v_mov_b32_e32 v221, v125
	v_mov_b32_e32 v220, v124
	v_mov_b32_e32 v223, v123
	v_mov_b32_e32 v222, v122
	v_mov_b64_e32 v[134:135], v[126:127]
	v_mov_b64_e32 v[132:133], v[124:125]
	v_mov_b64_e32 v[130:131], v[122:123]
.LBB0_397:
	s_andn2_b64 vcc, exec, s[2:3]
	s_cbranch_vccnz .LBB0_399
	v_and_b32_e32 v131, 64, v216
	v_xor_b32_e32 v130, 16, v216
	v_add_u32_e32 v131, 64, v131
	v_cmp_lt_i32_e32 vcc, v130, v131
	s_waitcnt vmcnt(4)
	v_mov_b32_e32 v131, v151
	v_mov_b32_e32 v135, v153
	v_cndmask_b32_e32 v130, v216, v130, vcc
	v_lshlrev_b32_e32 v162, 2, v130
	ds_bpermute_b32 v132, v162, v122
	ds_bpermute_b32 v134, v162, v123
	ds_bpermute_b32 v136, v162, v124
	v_mov_b32_e32 v130, v122
	ds_bpermute_b32 v174, v162, v126
	s_waitcnt lgkmcnt(3)
	v_cndmask_b32_e64 v133, v132, -v132, s[0:1]
	v_mov_b32_e32 v132, v150
	v_pk_mul_f32 v[130:131], v[130:131], v[132:133]
	s_waitcnt lgkmcnt(2)
	v_cndmask_b32_e64 v133, v134, -v134, s[0:1]
	v_mov_b32_e32 v134, v123
	v_mov_b32_e32 v132, v152
	v_pk_mul_f32 v[132:133], v[134:135], v[132:133]
	v_add_f32_e32 v130, v130, v131
	v_add_f32_e32 v131, v132, v133
	s_waitcnt lgkmcnt(1)
	v_cndmask_b32_e64 v133, v136, -v136, s[0:1]
	ds_bpermute_b32 v136, v162, v125
	v_mov_b32_e32 v134, v124
	v_mov_b32_e32 v135, v147
	v_mov_b32_e32 v132, v146
	v_pk_mul_f32 v[132:133], v[134:135], v[132:133]
	s_waitcnt lgkmcnt(0)
	v_cndmask_b32_e64 v135, v136, -v136, s[0:1]
	v_mov_b32_e32 v136, v125
	v_mov_b32_e32 v137, v149
	v_mov_b32_e32 v134, v148
	v_pk_mul_f32 v[134:135], v[136:137], v[134:135]
	v_add_f32_e32 v132, v132, v133
	v_add_f32_e32 v133, v134, v135
	v_cndmask_b32_e64 v135, v174, -v174, s[0:1]
	ds_bpermute_b32 v174, v162, v127
	ds_bpermute_b32 v176, v162, v128
	ds_bpermute_b32 v162, v162, v129
	v_mov_b32_e32 v136, v126
	v_mov_b32_e32 v137, v143
	v_mov_b32_e32 v134, v142
	v_pk_mul_f32 v[134:135], v[136:137], v[134:135]
	s_waitcnt lgkmcnt(2)
	v_cndmask_b32_e64 v137, v174, -v174, s[0:1]
	v_mov_b32_e32 v174, v127
	v_mov_b32_e32 v175, v145
	v_mov_b32_e32 v136, v144
	v_pk_mul_f32 v[136:137], v[174:175], v[136:137]
	v_add_f32_e32 v134, v134, v135
	v_add_f32_e32 v135, v136, v137
	s_waitcnt lgkmcnt(1)
	v_cndmask_b32_e64 v137, v176, -v176, s[0:1]
	v_mov_b32_e32 v174, v128
	v_mov_b32_e32 v175, v139
	v_mov_b32_e32 v136, v138
	v_pk_mul_f32 v[136:137], v[174:175], v[136:137]
	s_waitcnt lgkmcnt(0)
	v_cndmask_b32_e64 v175, v162, -v162, s[0:1]
	v_mov_b32_e32 v176, v129
	v_mov_b32_e32 v177, v141
	v_mov_b32_e32 v174, v140
	v_pk_mul_f32 v[174:175], v[176:177], v[174:175]
	v_add_f32_e32 v136, v136, v137
	v_add_f32_e32 v137, v174, v175
	v_cndmask_b32_e64 v130, v122, v130, s[10:11]
	v_cndmask_b32_e64 v131, v123, v131, s[10:11]
	v_cndmask_b32_e64 v132, v124, v132, s[10:11]
	v_cndmask_b32_e64 v133, v125, v133, s[10:11]
	v_cndmask_b32_e64 v134, v126, v134, s[10:11]
	v_cndmask_b32_e64 v135, v127, v135, s[10:11]
	v_cndmask_b32_e64 v136, v128, v136, s[10:11]
	v_cndmask_b32_e64 v137, v129, v137, s[10:11]
	v_mov_b32_e32 v222, v130
	v_mov_b32_e32 v223, v131
	v_mov_b32_e32 v220, v132
	v_mov_b32_e32 v221, v133
	v_mov_b32_e32 v181, v134
	v_mov_b32_e32 v219, v135
	v_mov_b32_e32 v178, v136
	v_mov_b32_e32 v179, v137

;     template <int MODE>
;     DI void rows(const pg8::f32x4 (&acc)[2][2][4][2], const pg8::Unit& u, int wr, int wc, int fr, int fq) const {
;     ...
;                 const int row = u.pm * 256 + ai * 128 + wr * 64 + m * 16 + fr;
;                 v2f cs[8];
;                 if constexpr (MODE <= 1) {
;                     const int pos = row < MP ? (row & (SEQ - 1)) : PAST + ((row - MP) & (DS - 1));
;                     const v4f* rp = (const v4f*)(rope + (size_t)pos * 8);
; #pragma unroll
;                     for (int i = 0; i < 4; ++i) { const v4f t = rp[i]; cs[2 * i] = (v2f){t.x, t.y}; cs[2 * i + 1] = (v2f){t.z, t.w}; }
;                 }
; #pragma unroll
;                 for (int bj = 0; bj < 2; ++bj) {
;                     float v[8];
; #pragma unroll
;                     for (int i = 0; i < 4; ++i) { v[i] = acc[ai][bj][m][0][i]; v[4 + i] = acc[ai][bj][m][1][i]; }
;                     const int col = pn * 256 + bj * 128 + tc0;
;                     if constexpr (MODE <= 1) {
;                         if ((wc & 1) == 0) {
;                             const float sgn = fq == 0 ? -1.f : 1.f;
; #pragma unroll
;                             for (int i = 0; i < 8; ++i) { const float pr = __shfl_xor(v[i], 16); const float r = v[i] * cs[i].x + sgn * pr * cs[i].y; v[i] = fq < 2 ? r : v[i]; }
;                         }
.LBB0_411:
	s_or_b64 exec, exec, s[2:3]
	v_or_b32_e32 v177, 16, v180
	v_bitop3_b32 v130, v180, s94, 16 bitop3:0xc8
	v_cmp_gt_i32_e64 s[8:9], s67, v177
	v_cmp_lt_i32_e64 s[6:7], s75, v177
	s_and_b64 vcc, exec, s[4:5]
	v_cndmask_b32_e64 v130, v200, v130, s[8:9]
	v_lshlrev_b32_e32 v130, 6, v130
	v_or_b32_e32 v245, 32, v180
	v_bitop3_b32 v244, v180, s95, 32 bitop3:0xc8
	v_cmp_gt_i32_e64 s[98:99], s67, v245
	v_cndmask_b32_e64 v244, v200, v244, s[98:99]
	v_lshlrev_b32_e32 v244, 6, v244
	global_load_dwordx4 v[138:141], v244, s[20:21] offset:48
	global_load_dwordx4 v[142:145], v244, s[20:21] offset:32
	global_load_dwordx4 v[146:149], v244, s[20:21] offset:16
	global_load_dwordx4 v[150:153], v244, s[20:21]
	s_mov_b64 s[2:3], -1
	s_cbranch_vccnz .LBB0_413
	v_mov_b64_e32 v[136:137], v[112:113]
	s_mov_b64 s[2:3], 0
	v_mov_b32_e32 v181, v113
	v_mov_b32_e32 v179, v112
	v_mov_b32_e32 v220, v111
	v_mov_b32_e32 v219, v110
	v_mov_b32_e32 v222, v109
	v_mov_b32_e32 v221, v108
	v_mov_b32_e32 v224, v107
	v_mov_b32_e32 v223, v106
	v_mov_b64_e32 v[134:135], v[110:111]
	v_mov_b64_e32 v[132:133], v[108:109]
	v_mov_b64_e32 v[130:131], v[106:107]
.LBB0_413:
	s_andn2_b64 vcc, exec, s[2:3]
	s_cbranch_vccnz .LBB0_415
	v_and_b32_e32 v131, 64, v216
	v_xor_b32_e32 v130, 16, v216
	v_add_u32_e32 v131, 64, v131
	v_cmp_lt_i32_e32 vcc, v130, v131
	s_waitcnt vmcnt(8)
	v_mov_b32_e32 v131, v241
	v_mov_b32_e32 v135, v243
	v_cndmask_b32_e32 v130, v216, v130, vcc
	v_lshlrev_b32_e32 v179, 2, v130
	ds_bpermute_b32 v132, v179, v106
	ds_bpermute_b32 v134, v179, v107
	ds_bpermute_b32 v136, v179, v108
	v_mov_b32_e32 v130, v106
	ds_bpermute_b32 v181, v179, v110
	s_waitcnt lgkmcnt(3)
	v_cndmask_b32_e64 v133, v132, -v132, s[0:1]
	v_mov_b32_e32 v132, v240
	v_pk_mul_f32 v[130:131], v[130:131], v[132:133]
	s_waitcnt lgkmcnt(2)
	v_cndmask_b32_e64 v133, v134, -v134, s[0:1]
	v_mov_b32_e32 v134, v107
	v_mov_b32_e32 v132, v242
	v_pk_mul_f32 v[132:133], v[134:135], v[132:133]
	v_add_f32_e32 v130, v130, v131
	v_add_f32_e32 v131, v132, v133
	s_waitcnt lgkmcnt(1)
	v_cndmask_b32_e64 v133, v136, -v136, s[0:1]
	ds_bpermute_b32 v136, v179, v109
	v_mov_b32_e32 v134, v108
	v_mov_b32_e32 v135, v237
	v_mov_b32_e32 v132, v236
	v_pk_mul_f32 v[132:133], v[134:135], v[132:133]
	s_waitcnt lgkmcnt(0)
	v_cndmask_b32_e64 v135, v136, -v136, s[0:1]
	v_mov_b32_e32 v136, v109
	v_mov_b32_e32 v137, v239
	v_mov_b32_e32 v134, v238
	v_pk_mul_f32 v[134:135], v[136:137], v[134:135]
	v_add_f32_e32 v132, v132, v133
	v_add_f32_e32 v133, v134, v135
	v_cndmask_b32_e64 v135, v181, -v181, s[0:1]
	ds_bpermute_b32 v181, v179, v111
	v_mov_b32_e32 v136, v110
	v_mov_b32_e32 v137, v233
	v_mov_b32_e32 v134, v232
	v_pk_mul_f32 v[134:135], v[136:137], v[134:135]
	s_waitcnt lgkmcnt(0)
	v_cndmask_b32_e64 v137, v181, -v181, s[0:1]
	ds_bpermute_b32 v181, v179, v112
	ds_bpermute_b32 v179, v179, v113
	v_mov_b32_e32 v182, v111
	v_mov_b32_e32 v183, v235
	v_mov_b32_e32 v136, v234
	v_pk_mul_f32 v[136:137], v[182:183], v[136:137]
	v_add_f32_e32 v134, v134, v135
	v_add_f32_e32 v135, v136, v137
	s_waitcnt lgkmcnt(1)
	v_cndmask_b32_e64 v137, v181, -v181, s[0:1]
	v_mov_b32_e32 v182, v112
	v_mov_b32_e32 v183, v229
	v_mov_b32_e32 v136, v228
	v_pk_mul_f32 v[136:137], v[182:183], v[136:137]
	s_waitcnt lgkmcnt(0)
	v_cndmask_b32_e64 v183, v179, -v179, s[0:1]
	v_mov_b32_e32 v184, v113
	v_mov_b32_e32 v185, v231
	v_mov_b32_e32 v182, v230
	v_pk_mul_f32 v[182:183], v[184:185], v[182:183]
	v_add_f32_e32 v136, v136, v137
	v_add_f32_e32 v137, v182, v183
	v_cndmask_b32_e64 v130, v106, v130, s[10:11]
	v_cndmask_b32_e64 v131, v107, v131, s[10:11]
	v_cndmask_b32_e64 v132, v108, v132, s[10:11]
	v_cndmask_b32_e64 v133, v109, v133, s[10:11]
	v_cndmask_b32_e64 v134, v110, v134, s[10:11]
	v_cndmask_b32_e64 v135, v111, v135, s[10:11]
	v_cndmask_b32_e64 v136, v112, v136, s[10:11]
	v_cndmask_b32_e64 v137, v113, v137, s[10:11]
	v_mov_b32_e32 v223, v130
	v_mov_b32_e32 v224, v131
	v_mov_b32_e32 v221, v132
	v_mov_b32_e32 v222, v133
	v_mov_b32_e32 v219, v134
	v_mov_b32_e32 v220, v135
	v_mov_b32_e32 v179, v136
	v_mov_b32_e32 v181, v137

; DI void st8f_nt(float* p, const float (&v)[8]) { __builtin_nontemporal_store((v4f){v[0], v[1], v[2], v[3]}, (v4f*)p); __builtin_nontemporal_store((v4f){v[4], v[5], v[6], v[7]}, (v4f*)(p + 4)); }
;     template <int MODE>
;     DI void rows(const pg8::f32x4 (&acc)[2][2][4][2], const pg8::Unit& u, int wr, int wc, int fr, int fq) const {
;     ...
;                     const int col = pn * 256 + bj * 128 + tc0;
;                     if constexpr (MODE <= 1) {
;                         if ((wc & 1) == 0) {
;                             const float sgn = fq == 0 ? -1.f : 1.f;
; #pragma unroll
;                             for (int i = 0; i < 8; ++i) { const float pr = __shfl_xor(v[i], 16); const float r = v[i] * cs[i].x + sgn * pr * cs[i].y; v[i] = fq < 2 ? r : v[i]; }
;                         }
;                         if constexpr (MODE == 0) {
; #pragma unroll
;                             for (int i = 0; i < 8; ++i) v[i] *= QA_SCALE;
;                         }
;                     }
;                     if constexpr (MODE == 1 || MODE == 2) {
;                         const int cs1 = (pn & 3) * 256 + bj * 128 + tc0;
;                         float* dst = row < MP ? out + (MODE == 1 ? O_KP : O_VP) + (size_t)row * 1024 + cs1 : out + (MODE == 1 ? O_KS : O_VS) + (size_t)(row - MP) * 1024 + cs1;
;                         st8f_nt(dst, v);
;     ...
;                     } else if constexpr (MODE == 1 || MODE == 2) {
;                         if (row < MP) {
;                             const int cc = (pn & 3) * 256 + bj * 128 + tc0, hd = cc >> 7;
;                             st8bf((MODE == 1 ? KC : VC) + ((size_t)((row >> 12) * 8 + hd) * SEQ + (row & (SEQ - 1))) * 128 + (cc & 127), v);
;                         } else st8bf(P + (size_t)row * PLD + col, v);
.LBB0_422:
	v_and_b32_e32 v131, 64, v216
	v_xor_b32_e32 v130, 16, v216
	v_add_u32_e32 v131, 64, v131
	v_cmp_lt_i32_e32 vcc, v130, v131
	s_waitcnt vmcnt(2)
	v_mov_b32_e32 v131, v241
	v_mov_b32_e32 v133, v243
	v_cndmask_b32_e32 v130, v216, v130, vcc
	v_lshlrev_b32_e32 v177, 2, v130
	ds_bpermute_b32 v130, v177, v98
	v_mov_b32_e32 v135, v239
	v_mov_b32_e32 v137, v235
	s_waitcnt lgkmcnt(0)
	v_cndmask_b32_e64 v132, v130, -v130, s[0:1]
	v_mov_b32_e32 v130, v98
	v_mov_b32_e32 v241, v132
	v_pk_mul_f32 v[130:131], v[130:131], v[240:241]
	v_mov_b32_e32 v132, v99
	v_add_f32_e32 v130, v130, v131
	ds_bpermute_b32 v131, v177, v99
	v_cndmask_b32_e64 v130, v98, v130, s[10:11]
	v_mov_b32_e32 v224, v130
	s_waitcnt lgkmcnt(0)
	v_cndmask_b32_e64 v131, v131, -v131, s[0:1]
	v_mov_b32_e32 v243, v131
	v_pk_mul_f32 v[132:133], v[132:133], v[242:243]
	s_nop 0
	v_add_f32_e32 v131, v132, v133
	ds_bpermute_b32 v132, v177, v100
	v_mov_b32_e32 v133, v237
	v_cndmask_b32_e64 v131, v99, v131, s[10:11]
	v_mov_b32_e32 v225, v131
	s_waitcnt lgkmcnt(0)
	v_cndmask_b32_e64 v134, v132, -v132, s[0:1]
	v_mov_b32_e32 v132, v100
	v_mov_b32_e32 v237, v134
	v_pk_mul_f32 v[132:133], v[132:133], v[236:237]
	v_mov_b32_e32 v134, v101
	v_add_f32_e32 v132, v132, v133
	ds_bpermute_b32 v133, v177, v101
	v_cndmask_b32_e64 v132, v100, v132, s[10:11]
	v_mov_b32_e32 v222, v132
	s_waitcnt lgkmcnt(0)
	v_cndmask_b32_e64 v133, v133, -v133, s[0:1]
	v_mov_b32_e32 v239, v133
	v_pk_mul_f32 v[134:135], v[134:135], v[238:239]
	s_nop 0
	v_add_f32_e32 v133, v134, v135
	ds_bpermute_b32 v134, v177, v102
	v_mov_b32_e32 v135, v233
	v_cndmask_b32_e64 v133, v101, v133, s[10:11]
	v_mov_b32_e32 v223, v133
	s_waitcnt lgkmcnt(0)
	v_cndmask_b32_e64 v136, v134, -v134, s[0:1]
	v_mov_b32_e32 v134, v102
	v_mov_b32_e32 v233, v136
	v_pk_mul_f32 v[134:135], v[134:135], v[232:233]
	v_mov_b32_e32 v136, v103
	v_add_f32_e32 v134, v134, v135
	ds_bpermute_b32 v135, v177, v103
	v_cndmask_b32_e64 v134, v102, v134, s[10:11]
	v_mov_b32_e32 v220, v134
	s_waitcnt lgkmcnt(0)
	v_cndmask_b32_e64 v135, v135, -v135, s[0:1]
	v_mov_b32_e32 v235, v135
	v_pk_mul_f32 v[136:137], v[136:137], v[234:235]
	s_nop 0
	v_add_f32_e32 v135, v136, v137
	ds_bpermute_b32 v136, v177, v104
	v_mov_b32_e32 v137, v229
	v_cndmask_b32_e64 v135, v103, v135, s[10:11]
	v_mov_b32_e32 v221, v135
	s_waitcnt lgkmcnt(0)
	v_cndmask_b32_e64 v232, v136, -v136, s[0:1]
	v_mov_b32_e32 v136, v104
	v_mov_b32_e32 v229, v232
	v_pk_mul_f32 v[136:137], v[136:137], v[228:229]
	v_mov_b32_e32 v228, v105
	v_add_f32_e32 v136, v136, v137
	ds_bpermute_b32 v137, v177, v105
	v_mov_b32_e32 v229, v231
	v_cndmask_b32_e64 v136, v104, v136, s[10:11]
	v_mov_b32_e32 v181, v136
	s_waitcnt lgkmcnt(0)
	v_cndmask_b32_e64 v137, v137, -v137, s[0:1]
	v_mov_b32_e32 v231, v137
	v_pk_mul_f32 v[228:229], v[228:229], v[230:231]
	s_nop 0
	v_add_f32_e32 v137, v228, v229
	v_cndmask_b32_e64 v137, v105, v137, s[10:11]
	v_mov_b32_e32 v219, v137
.LBB0_423:
	v_mov_b32_e32 v179, v163
	s_waitcnt vmcnt(5)
	v_lshl_add_u64 v[228:229], v[184:185], 0, v[178:179]
	global_store_dwordx4 v[228:229], v[130:133], off offset:512 nt
	global_store_dwordx4 v[228:229], v[134:137], off offset:528 nt
	s_and_saveexec_b64 s[2:3], s[6:7]
	s_xor_b64 s[2:3], exec, s[2:3]
	s_cbranch_execz .LBB0_425
	v_lshl_add_u64 v[134:135], v[174:175], 1, v[182:183]
	v_cvt_pk_bf16_f32 v130, v224, v225
	v_cvt_pk_bf16_f32 v131, v222, v223
	v_cvt_pk_bf16_f32 v132, v220, v221
	v_cvt_pk_bf16_f32 v133, v181, v219
	global_store_dwordx4 v[134:135], v[130:133], off offset:256

;     template <int MODE>
;     DI void rows(const pg8::f32x4 (&acc)[2][2][4][2], const pg8::Unit& u, int wr, int wc, int fr, int fq) const {
;     ...
;                 const int row = u.pm * 256 + ai * 128 + wr * 64 + m * 16 + fr;
;                 v2f cs[8];
;                 if constexpr (MODE <= 1) {
;                     const int pos = row < MP ? (row & (SEQ - 1)) : PAST + ((row - MP) & (DS - 1));
;                     const v4f* rp = (const v4f*)(rope + (size_t)pos * 8);
; #pragma unroll
;                     for (int i = 0; i < 4; ++i) { const v4f t = rp[i]; cs[2 * i] = (v2f){t.x, t.y}; cs[2 * i + 1] = (v2f){t.z, t.w}; }
;                 }
; #pragma unroll
;                 for (int bj = 0; bj < 2; ++bj) {
;                     float v[8];
; #pragma unroll
;                     for (int i = 0; i < 4; ++i) { v[i] = acc[ai][bj][m][0][i]; v[4 + i] = acc[ai][bj][m][1][i]; }
;                     const int col = pn * 256 + bj * 128 + tc0;
;                     if constexpr (MODE <= 1) {
;                         if ((wc & 1) == 0) {
;                             const float sgn = fq == 0 ? -1.f : 1.f;
; #pragma unroll
;                             for (int i = 0; i < 8; ++i) { const float pr = __shfl_xor(v[i], 16); const float r = v[i] * cs[i].x + sgn * pr * cs[i].y; v[i] = fq < 2 ? r : v[i]; }
;                         }
.LBB0_427:
	s_or_b64 exec, exec, s[2:3]
	v_or_b32_e32 v177, 32, v180
	v_bitop3_b32 v130, v180, s95, 32 bitop3:0xc8
	v_cmp_gt_i32_e64 s[8:9], s67, v177
	v_cmp_lt_i32_e64 s[6:7], s75, v177
	s_and_b64 vcc, exec, s[4:5]
	v_cndmask_b32_e64 v130, v200, v130, s[8:9]
	v_lshlrev_b32_e32 v130, 6, v130
	v_or_b32_e32 v245, 48, v180
	v_bitop3_b32 v244, v180, s73, 48 bitop3:0xc8
	v_cmp_gt_i32_e64 s[98:99], s67, v245
	v_cndmask_b32_e64 v244, v200, v244, s[98:99]
	v_lshlrev_b32_e32 v244, 6, v244
	global_load_dwordx4 v[228:231], v244, s[20:21] offset:48
	global_load_dwordx4 v[232:235], v244, s[20:21] offset:32
	global_load_dwordx4 v[236:239], v244, s[20:21] offset:16
	global_load_dwordx4 v[240:243], v244, s[20:21]
	s_mov_b64 s[2:3], -1
	s_cbranch_vccnz .LBB0_429
	v_mov_b64_e32 v[136:137], v[96:97]
	s_mov_b64 s[2:3], 0
	v_mov_b32_e32 v181, v97
	v_mov_b32_e32 v179, v96
	v_mov_b32_e32 v220, v95
	v_mov_b32_e32 v219, v94
	v_mov_b32_e32 v222, v93
	v_mov_b32_e32 v221, v92
	v_mov_b32_e32 v224, v91
	v_mov_b32_e32 v223, v90
	v_mov_b64_e32 v[134:135], v[94:95]
	v_mov_b64_e32 v[132:133], v[92:93]
	v_mov_b64_e32 v[130:131], v[90:91]
.LBB0_429:
	s_andn2_b64 vcc, exec, s[2:3]
	s_cbranch_vccnz .LBB0_431
	v_and_b32_e32 v131, 64, v216
	v_xor_b32_e32 v130, 16, v216
	v_add_u32_e32 v131, 64, v131
	v_cmp_lt_i32_e32 vcc, v130, v131
	s_waitcnt vmcnt(8)
	v_mov_b32_e32 v131, v151
	v_mov_b32_e32 v135, v153
	v_cndmask_b32_e32 v130, v216, v130, vcc
	v_lshlrev_b32_e32 v179, 2, v130
	ds_bpermute_b32 v132, v179, v90
	ds_bpermute_b32 v134, v179, v91
	ds_bpermute_b32 v136, v179, v92
	v_mov_b32_e32 v130, v90
	ds_bpermute_b32 v181, v179, v94
	s_waitcnt lgkmcnt(3)
	v_cndmask_b32_e64 v133, v132, -v132, s[0:1]
	v_mov_b32_e32 v132, v150
	v_pk_mul_f32 v[130:131], v[130:131], v[132:133]
	s_waitcnt lgkmcnt(2)
	v_cndmask_b32_e64 v133, v134, -v134, s[0:1]
	v_mov_b32_e32 v134, v91
	v_mov_b32_e32 v132, v152
	v_pk_mul_f32 v[132:133], v[134:135], v[132:133]
	v_add_f32_e32 v130, v130, v131
	v_add_f32_e32 v131, v132, v133
	s_waitcnt lgkmcnt(1)
	v_cndmask_b32_e64 v133, v136, -v136, s[0:1]
	ds_bpermute_b32 v136, v179, v93
	v_mov_b32_e32 v134, v92
	v_mov_b32_e32 v135, v147
	v_mov_b32_e32 v132, v146
	v_pk_mul_f32 v[132:133], v[134:135], v[132:133]
	s_waitcnt lgkmcnt(0)
	v_cndmask_b32_e64 v135, v136, -v136, s[0:1]
	v_mov_b32_e32 v136, v93
	v_mov_b32_e32 v137, v149
	v_mov_b32_e32 v134, v148
	v_pk_mul_f32 v[134:135], v[136:137], v[134:135]
	v_add_f32_e32 v132, v132, v133
	v_add_f32_e32 v133, v134, v135
	v_cndmask_b32_e64 v135, v181, -v181, s[0:1]
	ds_bpermute_b32 v181, v179, v95
	v_mov_b32_e32 v136, v94
	v_mov_b32_e32 v137, v143
	v_mov_b32_e32 v134, v142
	v_pk_mul_f32 v[134:135], v[136:137], v[134:135]
	s_waitcnt lgkmcnt(0)
	v_cndmask_b32_e64 v137, v181, -v181, s[0:1]
	ds_bpermute_b32 v181, v179, v96
	ds_bpermute_b32 v179, v179, v97
	v_mov_b32_e32 v182, v95
	v_mov_b32_e32 v183, v145
	v_mov_b32_e32 v136, v144
	v_pk_mul_f32 v[136:137], v[182:183], v[136:137]
	v_add_f32_e32 v134, v134, v135
	v_add_f32_e32 v135, v136, v137
	s_waitcnt lgkmcnt(1)
	v_cndmask_b32_e64 v137, v181, -v181, s[0:1]
	v_mov_b32_e32 v182, v96
	v_mov_b32_e32 v183, v139
	v_mov_b32_e32 v136, v138
	v_pk_mul_f32 v[136:137], v[182:183], v[136:137]
	s_waitcnt lgkmcnt(0)
	v_cndmask_b32_e64 v183, v179, -v179, s[0:1]
	v_mov_b32_e32 v184, v97
	v_mov_b32_e32 v185, v141
	v_mov_b32_e32 v182, v140
	v_pk_mul_f32 v[182:183], v[184:185], v[182:183]
	v_add_f32_e32 v136, v136, v137
	v_add_f32_e32 v137, v182, v183
	v_cndmask_b32_e64 v130, v90, v130, s[10:11]
	v_cndmask_b32_e64 v131, v91, v131, s[10:11]
	v_cndmask_b32_e64 v132, v92, v132, s[10:11]
	v_cndmask_b32_e64 v133, v93, v133, s[10:11]
	v_cndmask_b32_e64 v134, v94, v134, s[10:11]
	v_cndmask_b32_e64 v135, v95, v135, s[10:11]
	v_cndmask_b32_e64 v136, v96, v136, s[10:11]
	v_cndmask_b32_e64 v137, v97, v137, s[10:11]
	v_mov_b32_e32 v223, v130
	v_mov_b32_e32 v224, v131
	v_mov_b32_e32 v221, v132
	v_mov_b32_e32 v222, v133
	v_mov_b32_e32 v219, v134
	v_mov_b32_e32 v220, v135
	v_mov_b32_e32 v179, v136
	v_mov_b32_e32 v181, v137

;     template <int MODE>
;     DI void rows(const pg8::f32x4 (&acc)[2][2][4][2], const pg8::Unit& u, int wr, int wc, int fr, int fq) const {
;     ...
;                 const int row = u.pm * 256 + ai * 128 + wr * 64 + m * 16 + fr;
;                 v2f cs[8];
;                 if constexpr (MODE <= 1) {
;                     const int pos = row < MP ? (row & (SEQ - 1)) : PAST + ((row - MP) & (DS - 1));
;                     const v4f* rp = (const v4f*)(rope + (size_t)pos * 8);
; #pragma unroll
;                     for (int i = 0; i < 4; ++i) { const v4f t = rp[i]; cs[2 * i] = (v2f){t.x, t.y}; cs[2 * i + 1] = (v2f){t.z, t.w}; }
;                 }
; #pragma unroll
;                 for (int bj = 0; bj < 2; ++bj) {
;                     float v[8];
; #pragma unroll
;                     for (int i = 0; i < 4; ++i) { v[i] = acc[ai][bj][m][0][i]; v[4 + i] = acc[ai][bj][m][1][i]; }
;                     const int col = pn * 256 + bj * 128 + tc0;
;                     if constexpr (MODE <= 1) {
;                         if ((wc & 1) == 0) {
;                             const float sgn = fq == 0 ? -1.f : 1.f;
; #pragma unroll
;                             for (int i = 0; i < 8; ++i) { const float pr = __shfl_xor(v[i], 16); const float r = v[i] * cs[i].x + sgn * pr * cs[i].y; v[i] = fq < 2 ? r : v[i]; }
;                         }
.LBB0_443:
	s_or_b64 exec, exec, s[2:3]
	v_or_b32_e32 v177, 48, v180
	v_bitop3_b32 v130, v180, s73, 48 bitop3:0xc8
	v_cmp_gt_i32_e64 s[8:9], s67, v177
	v_cmp_lt_i32_e64 s[6:7], s75, v177
	s_and_b64 vcc, exec, s[4:5]
	v_cndmask_b32_e64 v130, v200, v130, s[8:9]
	v_lshlrev_b32_e32 v130, 6, v130
	s_add_i32 s100, s79, s70
	v_or_b32_e32 v245, s100, v1
	v_bitop3_b32 v244, s100, v215, v1 bitop3:0xc8
	v_cmp_gt_i32_e64 s[98:99], s67, v245
	v_cndmask_b32_e64 v244, v200, v244, s[98:99]
	v_lshlrev_b32_e32 v244, 6, v244
	global_load_dwordx4 v[138:141], v244, s[20:21] offset:48
	global_load_dwordx4 v[142:145], v244, s[20:21] offset:32
	global_load_dwordx4 v[146:149], v244, s[20:21] offset:16
	global_load_dwordx4 v[150:153], v244, s[20:21]
	s_mov_b64 s[2:3], -1
	s_cbranch_vccnz .LBB0_445
	v_mov_b64_e32 v[136:137], v[80:81]
	s_mov_b64 s[2:3], 0
	v_mov_b32_e32 v186, v81
	v_mov_b32_e32 v179, v80
	v_mov_b32_e32 v219, v79
	v_mov_b32_e32 v187, v78
	v_mov_b32_e32 v221, v77
	v_mov_b32_e32 v220, v76
	v_mov_b32_e32 v223, v75
	v_mov_b32_e32 v222, v74
	v_mov_b64_e32 v[134:135], v[78:79]
	v_mov_b64_e32 v[132:133], v[76:77]
	v_mov_b64_e32 v[130:131], v[74:75]
.LBB0_445:
	s_andn2_b64 vcc, exec, s[2:3]
	s_cbranch_vccnz .LBB0_447
	v_and_b32_e32 v131, 64, v216
	v_xor_b32_e32 v130, 16, v216
	v_add_u32_e32 v131, 64, v131
	v_cmp_lt_i32_e32 vcc, v130, v131
	s_waitcnt vmcnt(8)
	v_mov_b32_e32 v131, v241
	v_mov_b32_e32 v135, v243
	v_cndmask_b32_e32 v130, v216, v130, vcc
	v_lshlrev_b32_e32 v179, 2, v130
	ds_bpermute_b32 v132, v179, v74
	ds_bpermute_b32 v134, v179, v75
	ds_bpermute_b32 v136, v179, v76
	v_mov_b32_e32 v130, v74
	ds_bpermute_b32 v181, v179, v78
	s_waitcnt lgkmcnt(3)
	v_cndmask_b32_e64 v133, v132, -v132, s[0:1]
	v_mov_b32_e32 v132, v240
	v_pk_mul_f32 v[130:131], v[130:131], v[132:133]
	s_waitcnt lgkmcnt(2)
	v_cndmask_b32_e64 v133, v134, -v134, s[0:1]
	v_mov_b32_e32 v134, v75
	v_mov_b32_e32 v132, v242
	v_pk_mul_f32 v[132:133], v[134:135], v[132:133]
	v_add_f32_e32 v130, v130, v131
	v_add_f32_e32 v131, v132, v133
	s_waitcnt lgkmcnt(1)
	v_cndmask_b32_e64 v133, v136, -v136, s[0:1]
	ds_bpermute_b32 v136, v179, v77
	v_mov_b32_e32 v134, v76
	v_mov_b32_e32 v135, v237
	v_mov_b32_e32 v132, v236
	v_pk_mul_f32 v[132:133], v[134:135], v[132:133]
	s_waitcnt lgkmcnt(0)
	v_cndmask_b32_e64 v135, v136, -v136, s[0:1]
	v_mov_b32_e32 v136, v77
	v_mov_b32_e32 v137, v239
	v_mov_b32_e32 v134, v238
	v_pk_mul_f32 v[134:135], v[136:137], v[134:135]
	v_add_f32_e32 v132, v132, v133
	v_add_f32_e32 v133, v134, v135
	v_cndmask_b32_e64 v135, v181, -v181, s[0:1]
	ds_bpermute_b32 v181, v179, v79
	v_mov_b32_e32 v136, v78
	v_mov_b32_e32 v137, v233
	v_mov_b32_e32 v134, v232
	v_pk_mul_f32 v[134:135], v[136:137], v[134:135]
	s_waitcnt lgkmcnt(0)
	v_cndmask_b32_e64 v137, v181, -v181, s[0:1]
	ds_bpermute_b32 v181, v179, v80
	ds_bpermute_b32 v179, v179, v81
	v_mov_b32_e32 v182, v79
	v_mov_b32_e32 v183, v235
	v_mov_b32_e32 v136, v234
	v_pk_mul_f32 v[136:137], v[182:183], v[136:137]
	v_add_f32_e32 v134, v134, v135
	v_add_f32_e32 v135, v136, v137
	s_waitcnt lgkmcnt(1)
	v_cndmask_b32_e64 v137, v181, -v181, s[0:1]
	v_mov_b32_e32 v182, v80
	v_mov_b32_e32 v183, v229
	v_mov_b32_e32 v136, v228
	v_pk_mul_f32 v[136:137], v[182:183], v[136:137]
	s_waitcnt lgkmcnt(0)
	v_cndmask_b32_e64 v183, v179, -v179, s[0:1]
	v_mov_b32_e32 v184, v81
	v_mov_b32_e32 v185, v231
	v_mov_b32_e32 v182, v230
	v_pk_mul_f32 v[182:183], v[184:185], v[182:183]
	v_add_f32_e32 v136, v136, v137
	v_add_f32_e32 v137, v182, v183
	v_cndmask_b32_e64 v130, v74, v130, s[10:11]
	v_cndmask_b32_e64 v131, v75, v131, s[10:11]
	v_cndmask_b32_e64 v132, v76, v132, s[10:11]
	v_cndmask_b32_e64 v133, v77, v133, s[10:11]
	v_cndmask_b32_e64 v134, v78, v134, s[10:11]
	v_cndmask_b32_e64 v135, v79, v135, s[10:11]
	v_cndmask_b32_e64 v136, v80, v136, s[10:11]
	v_cndmask_b32_e64 v137, v81, v137, s[10:11]
	v_mov_b32_e32 v222, v130
	v_mov_b32_e32 v223, v131
	v_mov_b32_e32 v220, v132
	v_mov_b32_e32 v221, v133
	v_mov_b32_e32 v187, v134
	v_mov_b32_e32 v219, v135
	v_mov_b32_e32 v179, v136
	v_mov_b32_e32 v186, v137

; DI void st8f_nt(float* p, const float (&v)[8]) { __builtin_nontemporal_store((v4f){v[0], v[1], v[2], v[3]}, (v4f*)p); __builtin_nontemporal_store((v4f){v[4], v[5], v[6], v[7]}, (v4f*)(p + 4)); }
;     template <int MODE>
;     DI void rows(const pg8::f32x4 (&acc)[2][2][4][2], const pg8::Unit& u, int wr, int wc, int fr, int fq) const {
;     ...
;                     const int col = pn * 256 + bj * 128 + tc0;
;                     if constexpr (MODE <= 1) {
;                         if ((wc & 1) == 0) {
;                             const float sgn = fq == 0 ? -1.f : 1.f;
; #pragma unroll
;                             for (int i = 0; i < 8; ++i) { const float pr = __shfl_xor(v[i], 16); const float r = v[i] * cs[i].x + sgn * pr * cs[i].y; v[i] = fq < 2 ? r : v[i]; }
;                         }
;                         if constexpr (MODE == 0) {
; #pragma unroll
;                             for (int i = 0; i < 8; ++i) v[i] *= QA_SCALE;
;                         }
;                     }
;                     if constexpr (MODE == 1 || MODE == 2) {
;                         const int cs1 = (pn & 3) * 256 + bj * 128 + tc0;
;                         float* dst = row < MP ? out + (MODE == 1 ? O_KP : O_VP) + (size_t)row * 1024 + cs1 : out + (MODE == 1 ? O_KS : O_VS) + (size_t)(row - MP) * 1024 + cs1;
;                         st8f_nt(dst, v);
;     ...
;                     } else if constexpr (MODE == 1 || MODE == 2) {
;                         if (row < MP) {
;                             const int cc = (pn & 3) * 256 + bj * 128 + tc0, hd = cc >> 7;
;                             st8bf((MODE == 1 ? KC : VC) + ((size_t)((row >> 12) * 8 + hd) * SEQ + (row & (SEQ - 1))) * 128 + (cc & 127), v);
;                         } else st8bf(P + (size_t)row * PLD + col, v);
.LBB0_454:
	v_and_b32_e32 v131, 64, v216
	v_xor_b32_e32 v130, 16, v216
	v_add_u32_e32 v131, 64, v131
	v_cmp_lt_i32_e32 vcc, v130, v131
	s_waitcnt vmcnt(2)
	v_mov_b32_e32 v131, v241
	v_mov_b32_e32 v133, v243
	v_cndmask_b32_e32 v130, v216, v130, vcc
	v_lshlrev_b32_e32 v177, 2, v130
	ds_bpermute_b32 v130, v177, v66
	v_mov_b32_e32 v135, v239
	v_mov_b32_e32 v137, v235
	s_waitcnt lgkmcnt(0)
	v_cndmask_b32_e64 v132, v130, -v130, s[0:1]
	v_mov_b32_e32 v130, v66
	v_mov_b32_e32 v241, v132
	v_pk_mul_f32 v[130:131], v[130:131], v[240:241]
	v_mov_b32_e32 v132, v67
	v_add_f32_e32 v130, v130, v131
	ds_bpermute_b32 v131, v177, v67
	v_cndmask_b32_e64 v130, v66, v130, s[10:11]
	v_mov_b32_e32 v223, v130
	s_waitcnt lgkmcnt(0)
	v_cndmask_b32_e64 v131, v131, -v131, s[0:1]
	v_mov_b32_e32 v243, v131
	v_pk_mul_f32 v[132:133], v[132:133], v[242:243]
	s_nop 0
	v_add_f32_e32 v131, v132, v133
	ds_bpermute_b32 v132, v177, v68
	v_mov_b32_e32 v133, v237
	v_cndmask_b32_e64 v131, v67, v131, s[10:11]
	v_mov_b32_e32 v224, v131
	s_waitcnt lgkmcnt(0)
	v_cndmask_b32_e64 v134, v132, -v132, s[0:1]
	v_mov_b32_e32 v132, v68
	v_mov_b32_e32 v237, v134
	v_pk_mul_f32 v[132:133], v[132:133], v[236:237]
	v_mov_b32_e32 v134, v69
	v_add_f32_e32 v132, v132, v133
	ds_bpermute_b32 v133, v177, v69
	v_cndmask_b32_e64 v132, v68, v132, s[10:11]
	v_mov_b32_e32 v221, v132
	s_waitcnt lgkmcnt(0)
	v_cndmask_b32_e64 v133, v133, -v133, s[0:1]
	v_mov_b32_e32 v239, v133
	v_pk_mul_f32 v[134:135], v[134:135], v[238:239]
	s_nop 0
	v_add_f32_e32 v133, v134, v135
	ds_bpermute_b32 v134, v177, v70
	v_mov_b32_e32 v135, v233
	v_cndmask_b32_e64 v133, v69, v133, s[10:11]
	v_mov_b32_e32 v222, v133
	s_waitcnt lgkmcnt(0)
	v_cndmask_b32_e64 v136, v134, -v134, s[0:1]
	v_mov_b32_e32 v134, v70
	v_mov_b32_e32 v233, v136
	v_pk_mul_f32 v[134:135], v[134:135], v[232:233]
	v_mov_b32_e32 v136, v71
	v_add_f32_e32 v134, v134, v135
	ds_bpermute_b32 v135, v177, v71
	v_cndmask_b32_e64 v134, v70, v134, s[10:11]
	v_mov_b32_e32 v219, v134
	s_waitcnt lgkmcnt(0)
	v_cndmask_b32_e64 v135, v135, -v135, s[0:1]
	v_mov_b32_e32 v235, v135
	v_pk_mul_f32 v[136:137], v[136:137], v[234:235]
	s_nop 0
	v_add_f32_e32 v135, v136, v137
	ds_bpermute_b32 v136, v177, v72
	v_mov_b32_e32 v137, v229
	v_cndmask_b32_e64 v135, v71, v135, s[10:11]
	v_mov_b32_e32 v220, v135
	s_waitcnt lgkmcnt(0)
	v_cndmask_b32_e64 v232, v136, -v136, s[0:1]
	v_mov_b32_e32 v136, v72
	v_mov_b32_e32 v229, v232
	v_pk_mul_f32 v[136:137], v[136:137], v[228:229]
	v_mov_b32_e32 v228, v73
	v_add_f32_e32 v136, v136, v137
	ds_bpermute_b32 v137, v177, v73
	v_mov_b32_e32 v229, v231
	v_cndmask_b32_e64 v136, v72, v136, s[10:11]
	v_mov_b32_e32 v186, v136
	s_waitcnt lgkmcnt(0)
	v_cndmask_b32_e64 v137, v137, -v137, s[0:1]
	v_mov_b32_e32 v231, v137
	v_pk_mul_f32 v[228:229], v[228:229], v[230:231]
	s_nop 0
	v_add_f32_e32 v137, v228, v229
	v_cndmask_b32_e64 v137, v73, v137, s[10:11]
	v_mov_b32_e32 v187, v137
.LBB0_455:
	v_mov_b32_e32 v179, v163
	s_waitcnt vmcnt(5)
	v_lshl_add_u64 v[228:229], v[182:183], 0, v[178:179]
	global_store_dwordx4 v[228:229], v[130:133], off offset:512 nt
	global_store_dwordx4 v[228:229], v[134:137], off offset:528 nt
	s_and_saveexec_b64 s[2:3], s[6:7]
	s_xor_b64 s[2:3], exec, s[2:3]
	s_cbranch_execz .LBB0_457
	v_lshl_add_u64 v[134:135], v[174:175], 1, v[180:181]
	v_cvt_pk_bf16_f32 v130, v223, v224
	v_cvt_pk_bf16_f32 v131, v221, v222
	v_cvt_pk_bf16_f32 v132, v219, v220
	v_cvt_pk_bf16_f32 v133, v186, v187
	global_store_dwordx4 v[134:135], v[130:133], off offset:256

;     template <int MODE>
;     DI void rows(const pg8::f32x4 (&acc)[2][2][4][2], const pg8::Unit& u, int wr, int wc, int fr, int fq) const {
;     ...
;                 const int row = u.pm * 256 + ai * 128 + wr * 64 + m * 16 + fr;
;                 v2f cs[8];
;                 if constexpr (MODE <= 1) {
;                     const int pos = row < MP ? (row & (SEQ - 1)) : PAST + ((row - MP) & (DS - 1));
;                     const v4f* rp = (const v4f*)(rope + (size_t)pos * 8);
; #pragma unroll
;                     for (int i = 0; i < 4; ++i) { const v4f t = rp[i]; cs[2 * i] = (v2f){t.x, t.y}; cs[2 * i + 1] = (v2f){t.z, t.w}; }
;                 }
; #pragma unroll
;                 for (int bj = 0; bj < 2; ++bj) {
;                     float v[8];
; #pragma unroll
;                     for (int i = 0; i < 4; ++i) { v[i] = acc[ai][bj][m][0][i]; v[4 + i] = acc[ai][bj][m][1][i]; }
;                     const int col = pn * 256 + bj * 128 + tc0;
;                     if constexpr (MODE <= 1) {
;                         if ((wc & 1) == 0) {
;                             const float sgn = fq == 0 ? -1.f : 1.f;
; #pragma unroll
;                             for (int i = 0; i < 8; ++i) { const float pr = __shfl_xor(v[i], 16); const float r = v[i] * cs[i].x + sgn * pr * cs[i].y; v[i] = fq < 2 ? r : v[i]; }
;                         }
.LBB0_459:
	s_or_b64 exec, exec, s[2:3]
	s_add_i32 s79, s79, s70
	v_or_b32_e32 v180, s79, v1
	v_bitop3_b32 v130, s79, v215, v1 bitop3:0xc8
	v_cmp_gt_i32_e64 s[8:9], s67, v180
	v_cmp_lt_i32_e64 s[6:7], s75, v180
	s_and_b64 vcc, exec, s[4:5]
	v_cndmask_b32_e64 v130, v200, v130, s[8:9]
	v_lshlrev_b32_e32 v130, 6, v130
	v_or_b32_e32 v245, 16, v180
	v_bitop3_b32 v244, v180, s94, 16 bitop3:0xc8
	v_cmp_gt_i32_e64 s[98:99], s67, v245
	v_cndmask_b32_e64 v244, v200, v244, s[98:99]
	v_lshlrev_b32_e32 v244, 6, v244
	global_load_dwordx4 v[228:231], v244, s[20:21] offset:48
	global_load_dwordx4 v[232:235], v244, s[20:21] offset:32
	global_load_dwordx4 v[236:239], v244, s[20:21] offset:16
	global_load_dwordx4 v[240:243], v244, s[20:21]
	s_mov_b64 s[2:3], -1
	s_cbranch_vccnz .LBB0_461
	v_mov_b64_e32 v[136:137], v[64:65]
	s_mov_b64 s[2:3], 0
	v_mov_b32_e32 v181, v65
	v_mov_b32_e32 v179, v64
	v_mov_b32_e32 v220, v63
	v_mov_b32_e32 v219, v62
	v_mov_b32_e32 v222, v61
	v_mov_b32_e32 v221, v60
	v_mov_b32_e32 v224, v59
	v_mov_b32_e32 v223, v58
	v_mov_b64_e32 v[134:135], v[62:63]
	v_mov_b64_e32 v[132:133], v[60:61]
	v_mov_b64_e32 v[130:131], v[58:59]
.LBB0_461:
	s_andn2_b64 vcc, exec, s[2:3]
	s_cbranch_vccnz .LBB0_463
	v_and_b32_e32 v131, 64, v216
	v_xor_b32_e32 v130, 16, v216
	v_add_u32_e32 v131, 64, v131
	v_cmp_lt_i32_e32 vcc, v130, v131
	s_waitcnt vmcnt(8)
	v_mov_b32_e32 v131, v151
	v_mov_b32_e32 v135, v153
	v_cndmask_b32_e32 v130, v216, v130, vcc
	v_lshlrev_b32_e32 v177, 2, v130
	ds_bpermute_b32 v132, v177, v58
	ds_bpermute_b32 v134, v177, v59
	ds_bpermute_b32 v136, v177, v60
	v_mov_b32_e32 v130, v58
	ds_bpermute_b32 v179, v177, v62
	s_waitcnt lgkmcnt(3)
	v_cndmask_b32_e64 v133, v132, -v132, s[0:1]
	v_mov_b32_e32 v132, v150
	v_pk_mul_f32 v[130:131], v[130:131], v[132:133]
	s_waitcnt lgkmcnt(2)
	v_cndmask_b32_e64 v133, v134, -v134, s[0:1]
	v_mov_b32_e32 v134, v59
	v_mov_b32_e32 v132, v152
	v_pk_mul_f32 v[132:133], v[134:135], v[132:133]
	v_add_f32_e32 v130, v130, v131
	v_add_f32_e32 v131, v132, v133
	s_waitcnt lgkmcnt(1)
	v_cndmask_b32_e64 v133, v136, -v136, s[0:1]
	ds_bpermute_b32 v136, v177, v61
	v_mov_b32_e32 v134, v60
	v_mov_b32_e32 v135, v147
	v_mov_b32_e32 v132, v146
	v_pk_mul_f32 v[132:133], v[134:135], v[132:133]
	s_waitcnt lgkmcnt(0)
	v_cndmask_b32_e64 v135, v136, -v136, s[0:1]
	v_mov_b32_e32 v136, v61
	v_mov_b32_e32 v137, v149
	v_mov_b32_e32 v134, v148
	v_pk_mul_f32 v[134:135], v[136:137], v[134:135]
	v_add_f32_e32 v132, v132, v133
	v_add_f32_e32 v133, v134, v135
	v_cndmask_b32_e64 v135, v179, -v179, s[0:1]
	ds_bpermute_b32 v179, v177, v63
	v_mov_b32_e32 v136, v62
	v_mov_b32_e32 v137, v143
	v_mov_b32_e32 v134, v142
	v_pk_mul_f32 v[134:135], v[136:137], v[134:135]
	s_waitcnt lgkmcnt(0)
	v_cndmask_b32_e64 v137, v179, -v179, s[0:1]
	ds_bpermute_b32 v179, v177, v64
	ds_bpermute_b32 v177, v177, v65
	v_mov_b32_e32 v182, v63
	v_mov_b32_e32 v183, v145
	v_mov_b32_e32 v136, v144
	v_pk_mul_f32 v[136:137], v[182:183], v[136:137]
	v_add_f32_e32 v134, v134, v135
	v_add_f32_e32 v135, v136, v137
	s_waitcnt lgkmcnt(1)
	v_cndmask_b32_e64 v137, v179, -v179, s[0:1]
	v_mov_b32_e32 v182, v64
	v_mov_b32_e32 v183, v139
	v_mov_b32_e32 v136, v138
	v_pk_mul_f32 v[136:137], v[182:183], v[136:137]
	s_waitcnt lgkmcnt(0)
	v_cndmask_b32_e64 v183, v177, -v177, s[0:1]
	v_mov_b32_e32 v184, v65
	v_mov_b32_e32 v185, v141
	v_mov_b32_e32 v182, v140
	v_pk_mul_f32 v[182:183], v[184:185], v[182:183]
	v_add_f32_e32 v136, v136, v137
	v_add_f32_e32 v137, v182, v183
	v_cndmask_b32_e64 v130, v58, v130, s[10:11]
	v_cndmask_b32_e64 v131, v59, v131, s[10:11]
	v_cndmask_b32_e64 v132, v60, v132, s[10:11]
	v_cndmask_b32_e64 v133, v61, v133, s[10:11]
	v_cndmask_b32_e64 v134, v62, v134, s[10:11]
	v_cndmask_b32_e64 v135, v63, v135, s[10:11]
	v_cndmask_b32_e64 v136, v64, v136, s[10:11]
	v_cndmask_b32_e64 v137, v65, v137, s[10:11]
	v_mov_b32_e32 v223, v130
	v_mov_b32_e32 v224, v131
	v_mov_b32_e32 v221, v132
	v_mov_b32_e32 v222, v133
	v_mov_b32_e32 v219, v134
	v_mov_b32_e32 v220, v135
	v_mov_b32_e32 v179, v136
	v_mov_b32_e32 v181, v137

;     template <int MODE>
;     DI void rows(const pg8::f32x4 (&acc)[2][2][4][2], const pg8::Unit& u, int wr, int wc, int fr, int fq) const {
;     ...
;                 const int row = u.pm * 256 + ai * 128 + wr * 64 + m * 16 + fr;
;                 v2f cs[8];
;                 if constexpr (MODE <= 1) {
;                     const int pos = row < MP ? (row & (SEQ - 1)) : PAST + ((row - MP) & (DS - 1));
;                     const v4f* rp = (const v4f*)(rope + (size_t)pos * 8);
; #pragma unroll
;                     for (int i = 0; i < 4; ++i) { const v4f t = rp[i]; cs[2 * i] = (v2f){t.x, t.y}; cs[2 * i + 1] = (v2f){t.z, t.w}; }
;                 }
; #pragma unroll
;                 for (int bj = 0; bj < 2; ++bj) {
;                     float v[8];
; #pragma unroll
;                     for (int i = 0; i < 4; ++i) { v[i] = acc[ai][bj][m][0][i]; v[4 + i] = acc[ai][bj][m][1][i]; }
;                     const int col = pn * 256 + bj * 128 + tc0;
;                     if constexpr (MODE <= 1) {
;                         if ((wc & 1) == 0) {
;                             const float sgn = fq == 0 ? -1.f : 1.f;
; #pragma unroll
;                             for (int i = 0; i < 8; ++i) { const float pr = __shfl_xor(v[i], 16); const float r = v[i] * cs[i].x + sgn * pr * cs[i].y; v[i] = fq < 2 ? r : v[i]; }
;                         }
.LBB0_475:
	s_or_b64 exec, exec, s[2:3]
	v_or_b32_e32 v177, 16, v180
	v_bitop3_b32 v130, v180, s94, 16 bitop3:0xc8
	v_cmp_gt_i32_e64 s[8:9], s67, v177
	v_cmp_lt_i32_e64 s[6:7], s75, v177
	s_and_b64 vcc, exec, s[4:5]
	v_cndmask_b32_e64 v130, v200, v130, s[8:9]
	v_lshlrev_b32_e32 v130, 6, v130
	v_or_b32_e32 v245, 32, v180
	v_bitop3_b32 v244, v180, s95, 32 bitop3:0xc8
	v_cmp_gt_i32_e64 s[98:99], s67, v245
	v_cndmask_b32_e64 v244, v200, v244, s[98:99]
	v_lshlrev_b32_e32 v244, 6, v244
	global_load_dwordx4 v[138:141], v244, s[20:21] offset:48
	global_load_dwordx4 v[142:145], v244, s[20:21] offset:32
	global_load_dwordx4 v[146:149], v244, s[20:21] offset:16
	global_load_dwordx4 v[150:153], v244, s[20:21]
	s_mov_b64 s[2:3], -1
	s_cbranch_vccnz .LBB0_477
	v_mov_b64_e32 v[136:137], v[48:49]
	s_mov_b64 s[2:3], 0
	v_mov_b32_e32 v181, v49
	v_mov_b32_e32 v179, v48
	v_mov_b32_e32 v220, v47
	v_mov_b32_e32 v219, v46
	v_mov_b32_e32 v222, v45
	v_mov_b32_e32 v221, v44
	v_mov_b32_e32 v224, v43
	v_mov_b32_e32 v223, v42
	v_mov_b64_e32 v[134:135], v[46:47]
	v_mov_b64_e32 v[132:133], v[44:45]
	v_mov_b64_e32 v[130:131], v[42:43]
.LBB0_477:
	s_andn2_b64 vcc, exec, s[2:3]
	s_cbranch_vccnz .LBB0_479
	v_and_b32_e32 v131, 64, v216
	v_xor_b32_e32 v130, 16, v216
	v_add_u32_e32 v131, 64, v131
	v_cmp_lt_i32_e32 vcc, v130, v131
	s_waitcnt vmcnt(8)
	v_mov_b32_e32 v131, v241
	v_mov_b32_e32 v135, v243
	v_cndmask_b32_e32 v130, v216, v130, vcc
	v_lshlrev_b32_e32 v179, 2, v130
	ds_bpermute_b32 v132, v179, v42
	ds_bpermute_b32 v134, v179, v43
	ds_bpermute_b32 v136, v179, v44
	v_mov_b32_e32 v130, v42
	ds_bpermute_b32 v181, v179, v46
	s_waitcnt lgkmcnt(3)
	v_cndmask_b32_e64 v133, v132, -v132, s[0:1]
	v_mov_b32_e32 v132, v240
	v_pk_mul_f32 v[130:131], v[130:131], v[132:133]
	s_waitcnt lgkmcnt(2)
	v_cndmask_b32_e64 v133, v134, -v134, s[0:1]
	v_mov_b32_e32 v134, v43
	v_mov_b32_e32 v132, v242
	v_pk_mul_f32 v[132:133], v[134:135], v[132:133]
	v_add_f32_e32 v130, v130, v131
	v_add_f32_e32 v131, v132, v133
	s_waitcnt lgkmcnt(1)
	v_cndmask_b32_e64 v133, v136, -v136, s[0:1]
	ds_bpermute_b32 v136, v179, v45
	v_mov_b32_e32 v134, v44
	v_mov_b32_e32 v135, v237
	v_mov_b32_e32 v132, v236
	v_pk_mul_f32 v[132:133], v[134:135], v[132:133]
	s_waitcnt lgkmcnt(0)
	v_cndmask_b32_e64 v135, v136, -v136, s[0:1]
	v_mov_b32_e32 v136, v45
	v_mov_b32_e32 v137, v239
	v_mov_b32_e32 v134, v238
	v_pk_mul_f32 v[134:135], v[136:137], v[134:135]
	v_add_f32_e32 v132, v132, v133
	v_add_f32_e32 v133, v134, v135
	v_cndmask_b32_e64 v135, v181, -v181, s[0:1]
	ds_bpermute_b32 v181, v179, v47
	v_mov_b32_e32 v136, v46
	v_mov_b32_e32 v137, v233
	v_mov_b32_e32 v134, v232
	v_pk_mul_f32 v[134:135], v[136:137], v[134:135]
	s_waitcnt lgkmcnt(0)
	v_cndmask_b32_e64 v137, v181, -v181, s[0:1]
	ds_bpermute_b32 v181, v179, v48
	ds_bpermute_b32 v179, v179, v49
	v_mov_b32_e32 v182, v47
	v_mov_b32_e32 v183, v235
	v_mov_b32_e32 v136, v234
	v_pk_mul_f32 v[136:137], v[182:183], v[136:137]
	v_add_f32_e32 v134, v134, v135
	v_add_f32_e32 v135, v136, v137
	s_waitcnt lgkmcnt(1)
	v_cndmask_b32_e64 v137, v181, -v181, s[0:1]
	v_mov_b32_e32 v182, v48
	v_mov_b32_e32 v183, v229
	v_mov_b32_e32 v136, v228
	v_pk_mul_f32 v[136:137], v[182:183], v[136:137]
	s_waitcnt lgkmcnt(0)
	v_cndmask_b32_e64 v183, v179, -v179, s[0:1]
	v_mov_b32_e32 v184, v49
	v_mov_b32_e32 v185, v231
	v_mov_b32_e32 v182, v230
	v_pk_mul_f32 v[182:183], v[184:185], v[182:183]
	v_add_f32_e32 v136, v136, v137
	v_add_f32_e32 v137, v182, v183
	v_cndmask_b32_e64 v130, v42, v130, s[10:11]
	v_cndmask_b32_e64 v131, v43, v131, s[10:11]
	v_cndmask_b32_e64 v132, v44, v132, s[10:11]
	v_cndmask_b32_e64 v133, v45, v133, s[10:11]
	v_cndmask_b32_e64 v134, v46, v134, s[10:11]
	v_cndmask_b32_e64 v135, v47, v135, s[10:11]
	v_cndmask_b32_e64 v136, v48, v136, s[10:11]
	v_cndmask_b32_e64 v137, v49, v137, s[10:11]
	v_mov_b32_e32 v223, v130
	v_mov_b32_e32 v224, v131
	v_mov_b32_e32 v221, v132
	v_mov_b32_e32 v222, v133
	v_mov_b32_e32 v219, v134
	v_mov_b32_e32 v220, v135
	v_mov_b32_e32 v179, v136
	v_mov_b32_e32 v181, v137

;     template <int MODE>
;     DI void rows(const pg8::f32x4 (&acc)[2][2][4][2], const pg8::Unit& u, int wr, int wc, int fr, int fq) const {
;     ...
;                 for (int bj = 0; bj < 2; ++bj) {
;                     float v[8];
; #pragma unroll
;                     for (int i = 0; i < 4; ++i) { v[i] = acc[ai][bj][m][0][i]; v[4 + i] = acc[ai][bj][m][1][i]; }
;                     const int col = pn * 256 + bj * 128 + tc0;
;                     if constexpr (MODE <= 1) {
;                         if ((wc & 1) == 0) {
;                             const float sgn = fq == 0 ? -1.f : 1.f;
; #pragma unroll
;                             for (int i = 0; i < 8; ++i) { const float pr = __shfl_xor(v[i], 16); const float r = v[i] * cs[i].x + sgn * pr * cs[i].y; v[i] = fq < 2 ? r : v[i]; }
;                         }
.LBB0_486:
	v_and_b32_e32 v131, 64, v216
	v_xor_b32_e32 v130, 16, v216
	v_add_u32_e32 v131, 64, v131
	v_cmp_lt_i32_e32 vcc, v130, v131
	s_waitcnt vmcnt(2)
	v_mov_b32_e32 v131, v241
	v_mov_b32_e32 v133, v243
	v_cndmask_b32_e32 v130, v216, v130, vcc
	v_lshlrev_b32_e32 v177, 2, v130
	ds_bpermute_b32 v130, v177, v34
	v_mov_b32_e32 v135, v239
	v_mov_b32_e32 v137, v235
	s_waitcnt lgkmcnt(0)
	v_cndmask_b32_e64 v132, v130, -v130, s[0:1]
	v_mov_b32_e32 v130, v34
	v_mov_b32_e32 v241, v132
	v_pk_mul_f32 v[130:131], v[130:131], v[240:241]
	v_mov_b32_e32 v132, v35
	v_add_f32_e32 v130, v130, v131
	ds_bpermute_b32 v131, v177, v35
	v_cndmask_b32_e64 v130, v34, v130, s[10:11]
	v_mov_b32_e32 v224, v130
	s_waitcnt lgkmcnt(0)
	v_cndmask_b32_e64 v131, v131, -v131, s[0:1]
	v_mov_b32_e32 v243, v131
	v_pk_mul_f32 v[132:133], v[132:133], v[242:243]
	s_nop 0
	v_add_f32_e32 v131, v132, v133
	ds_bpermute_b32 v132, v177, v36
	v_mov_b32_e32 v133, v237
	v_cndmask_b32_e64 v131, v35, v131, s[10:11]
	v_mov_b32_e32 v225, v131
	s_waitcnt lgkmcnt(0)
	v_cndmask_b32_e64 v134, v132, -v132, s[0:1]
	v_mov_b32_e32 v132, v36
	v_mov_b32_e32 v237, v134
	v_pk_mul_f32 v[132:133], v[132:133], v[236:237]
	v_mov_b32_e32 v134, v37
	v_add_f32_e32 v132, v132, v133
	ds_bpermute_b32 v133, v177, v37
	v_cndmask_b32_e64 v132, v36, v132, s[10:11]
	v_mov_b32_e32 v222, v132
	s_waitcnt lgkmcnt(0)
	v_cndmask_b32_e64 v133, v133, -v133, s[0:1]
	v_mov_b32_e32 v239, v133
	v_pk_mul_f32 v[134:135], v[134:135], v[238:239]
	s_nop 0
	v_add_f32_e32 v133, v134, v135
	ds_bpermute_b32 v134, v177, v38
	v_mov_b32_e32 v135, v233
	v_cndmask_b32_e64 v133, v37, v133, s[10:11]
	v_mov_b32_e32 v223, v133
	s_waitcnt lgkmcnt(0)
	v_cndmask_b32_e64 v136, v134, -v134, s[0:1]
	v_mov_b32_e32 v134, v38
	v_mov_b32_e32 v233, v136
	v_pk_mul_f32 v[134:135], v[134:135], v[232:233]
	v_mov_b32_e32 v136, v39
	v_add_f32_e32 v134, v134, v135
	ds_bpermute_b32 v135, v177, v39
	v_cndmask_b32_e64 v134, v38, v134, s[10:11]
	v_mov_b32_e32 v220, v134
	s_waitcnt lgkmcnt(0)
	v_cndmask_b32_e64 v135, v135, -v135, s[0:1]
	v_mov_b32_e32 v235, v135
	v_pk_mul_f32 v[136:137], v[136:137], v[234:235]
	s_nop 0
	v_add_f32_e32 v135, v136, v137
	ds_bpermute_b32 v136, v177, v40
	v_mov_b32_e32 v137, v229
	v_cndmask_b32_e64 v135, v39, v135, s[10:11]
	v_mov_b32_e32 v221, v135
	s_waitcnt lgkmcnt(0)
	v_cndmask_b32_e64 v232, v136, -v136, s[0:1]
	v_mov_b32_e32 v136, v40
	v_mov_b32_e32 v229, v232
	v_pk_mul_f32 v[136:137], v[136:137], v[228:229]
	v_mov_b32_e32 v228, v41
	v_add_f32_e32 v136, v136, v137
	ds_bpermute_b32 v137, v177, v41
	v_mov_b32_e32 v229, v231
	v_cndmask_b32_e64 v136, v40, v136, s[10:11]
	v_mov_b32_e32 v181, v136
	s_waitcnt lgkmcnt(0)
	v_cndmask_b32_e64 v137, v137, -v137, s[0:1]
	v_mov_b32_e32 v231, v137
	v_pk_mul_f32 v[228:229], v[228:229], v[230:231]
	s_nop 0
	v_add_f32_e32 v137, v228, v229
	v_cndmask_b32_e64 v137, v41, v137, s[10:11]
	v_mov_b32_e32 v219, v137

;     template <int MODE>
;     DI void rows(const pg8::f32x4 (&acc)[2][2][4][2], const pg8::Unit& u, int wr, int wc, int fr, int fq) const {
;     ...
;                 const int row = u.pm * 256 + ai * 128 + wr * 64 + m * 16 + fr;
;                 v2f cs[8];
;                 if constexpr (MODE <= 1) {
;                     const int pos = row < MP ? (row & (SEQ - 1)) : PAST + ((row - MP) & (DS - 1));
;                     const v4f* rp = (const v4f*)(rope + (size_t)pos * 8);
; #pragma unroll
;                     for (int i = 0; i < 4; ++i) { const v4f t = rp[i]; cs[2 * i] = (v2f){t.x, t.y}; cs[2 * i + 1] = (v2f){t.z, t.w}; }
;                 }
; #pragma unroll
;                 for (int bj = 0; bj < 2; ++bj) {
;                     float v[8];
; #pragma unroll
;                     for (int i = 0; i < 4; ++i) { v[i] = acc[ai][bj][m][0][i]; v[4 + i] = acc[ai][bj][m][1][i]; }
;                     const int col = pn * 256 + bj * 128 + tc0;
;                     if constexpr (MODE <= 1) {
;                         if ((wc & 1) == 0) {
;                             const float sgn = fq == 0 ? -1.f : 1.f;
; #pragma unroll
;                             for (int i = 0; i < 8; ++i) { const float pr = __shfl_xor(v[i], 16); const float r = v[i] * cs[i].x + sgn * pr * cs[i].y; v[i] = fq < 2 ? r : v[i]; }
;                         }
.LBB0_491:
	s_or_b64 exec, exec, s[2:3]
	v_or_b32_e32 v177, 32, v180
	v_bitop3_b32 v130, v180, s95, 32 bitop3:0xc8
	v_cmp_gt_i32_e64 s[8:9], s67, v177
	v_cmp_lt_i32_e64 s[6:7], s75, v177
	s_and_b64 vcc, exec, s[4:5]
	v_cndmask_b32_e64 v130, v200, v130, s[8:9]
	v_lshlrev_b32_e32 v130, 6, v130
	v_or_b32_e32 v245, 48, v180
	v_bitop3_b32 v244, v180, s73, 48 bitop3:0xc8
	v_cmp_gt_i32_e64 s[98:99], s67, v245
	v_cndmask_b32_e64 v244, v200, v244, s[98:99]
	v_lshlrev_b32_e32 v244, 6, v244
	global_load_dwordx4 v[228:231], v244, s[20:21] offset:48
	global_load_dwordx4 v[232:235], v244, s[20:21] offset:32
	global_load_dwordx4 v[236:239], v244, s[20:21] offset:16
	global_load_dwordx4 v[240:243], v244, s[20:21]
	s_mov_b64 s[2:3], -1
	s_cbranch_vccnz .LBB0_493
	v_mov_b64_e32 v[136:137], v[32:33]
	s_mov_b64 s[2:3], 0
	v_mov_b32_e32 v181, v33
	v_mov_b32_e32 v179, v32
	v_mov_b32_e32 v220, v31
	v_mov_b32_e32 v219, v30
	v_mov_b32_e32 v222, v29
	v_mov_b32_e32 v221, v28
	v_mov_b32_e32 v224, v27
	v_mov_b32_e32 v223, v26
	v_mov_b64_e32 v[134:135], v[30:31]
	v_mov_b64_e32 v[132:133], v[28:29]
	v_mov_b64_e32 v[130:131], v[26:27]
.LBB0_493:
	s_andn2_b64 vcc, exec, s[2:3]
	s_cbranch_vccnz .LBB0_495
	v_and_b32_e32 v131, 64, v216
	v_xor_b32_e32 v130, 16, v216
	v_add_u32_e32 v131, 64, v131
	v_cmp_lt_i32_e32 vcc, v130, v131
	s_waitcnt vmcnt(8)
	v_mov_b32_e32 v131, v151
	v_mov_b32_e32 v135, v153
	v_cndmask_b32_e32 v130, v216, v130, vcc
	v_lshlrev_b32_e32 v179, 2, v130
	ds_bpermute_b32 v132, v179, v26
	ds_bpermute_b32 v134, v179, v27
	ds_bpermute_b32 v136, v179, v28
	v_mov_b32_e32 v130, v26
	ds_bpermute_b32 v181, v179, v30
	s_waitcnt lgkmcnt(3)
	v_cndmask_b32_e64 v133, v132, -v132, s[0:1]
	v_mov_b32_e32 v132, v150
	v_pk_mul_f32 v[130:131], v[130:131], v[132:133]
	s_waitcnt lgkmcnt(2)
	v_cndmask_b32_e64 v133, v134, -v134, s[0:1]
	v_mov_b32_e32 v134, v27
	v_mov_b32_e32 v132, v152
	v_pk_mul_f32 v[132:133], v[134:135], v[132:133]
	v_add_f32_e32 v130, v130, v131
	v_add_f32_e32 v131, v132, v133
	s_waitcnt lgkmcnt(1)
	v_cndmask_b32_e64 v133, v136, -v136, s[0:1]
	ds_bpermute_b32 v136, v179, v29
	v_mov_b32_e32 v134, v28
	v_mov_b32_e32 v135, v147
	v_mov_b32_e32 v132, v146
	v_pk_mul_f32 v[132:133], v[134:135], v[132:133]
	s_waitcnt lgkmcnt(0)
	v_cndmask_b32_e64 v135, v136, -v136, s[0:1]
	v_mov_b32_e32 v136, v29
	v_mov_b32_e32 v137, v149
	v_mov_b32_e32 v134, v148
	v_pk_mul_f32 v[134:135], v[136:137], v[134:135]
	v_add_f32_e32 v132, v132, v133
	v_add_f32_e32 v133, v134, v135
	v_cndmask_b32_e64 v135, v181, -v181, s[0:1]
	ds_bpermute_b32 v181, v179, v31
	v_mov_b32_e32 v136, v30
	v_mov_b32_e32 v137, v143
	v_mov_b32_e32 v134, v142
	v_pk_mul_f32 v[134:135], v[136:137], v[134:135]
	s_waitcnt lgkmcnt(0)
	v_cndmask_b32_e64 v137, v181, -v181, s[0:1]
	ds_bpermute_b32 v181, v179, v32
	ds_bpermute_b32 v179, v179, v33
	v_mov_b32_e32 v182, v31
	v_mov_b32_e32 v183, v145
	v_mov_b32_e32 v136, v144
	v_pk_mul_f32 v[136:137], v[182:183], v[136:137]
	v_add_f32_e32 v134, v134, v135
	v_add_f32_e32 v135, v136, v137
	s_waitcnt lgkmcnt(1)
	v_cndmask_b32_e64 v137, v181, -v181, s[0:1]
	v_mov_b32_e32 v182, v32
	v_mov_b32_e32 v183, v139
	v_mov_b32_e32 v136, v138
	v_pk_mul_f32 v[136:137], v[182:183], v[136:137]
	s_waitcnt lgkmcnt(0)
	v_cndmask_b32_e64 v183, v179, -v179, s[0:1]
	v_mov_b32_e32 v184, v33
	v_mov_b32_e32 v185, v141
	v_mov_b32_e32 v182, v140
	v_pk_mul_f32 v[182:183], v[184:185], v[182:183]
	v_add_f32_e32 v136, v136, v137
	v_add_f32_e32 v137, v182, v183
	v_cndmask_b32_e64 v130, v26, v130, s[10:11]
	v_cndmask_b32_e64 v131, v27, v131, s[10:11]
	v_cndmask_b32_e64 v132, v28, v132, s[10:11]
	v_cndmask_b32_e64 v133, v29, v133, s[10:11]
	v_cndmask_b32_e64 v134, v30, v134, s[10:11]
	v_cndmask_b32_e64 v135, v31, v135, s[10:11]
	v_cndmask_b32_e64 v136, v32, v136, s[10:11]
	v_cndmask_b32_e64 v137, v33, v137, s[10:11]
	v_mov_b32_e32 v223, v130
	v_mov_b32_e32 v224, v131
	v_mov_b32_e32 v221, v132
	v_mov_b32_e32 v222, v133
	v_mov_b32_e32 v219, v134
	v_mov_b32_e32 v220, v135
	v_mov_b32_e32 v179, v136
	v_mov_b32_e32 v181, v137

;     template <int MODE>
;     DI void rows(const pg8::f32x4 (&acc)[2][2][4][2], const pg8::Unit& u, int wr, int wc, int fr, int fq) const {
;     ...
;                 const int row = u.pm * 256 + ai * 128 + wr * 64 + m * 16 + fr;
;                 v2f cs[8];
;                 if constexpr (MODE <= 1) {
;                     const int pos = row < MP ? (row & (SEQ - 1)) : PAST + ((row - MP) & (DS - 1));
;                     const v4f* rp = (const v4f*)(rope + (size_t)pos * 8);
; #pragma unroll
;                     for (int i = 0; i < 4; ++i) { const v4f t = rp[i]; cs[2 * i] = (v2f){t.x, t.y}; cs[2 * i + 1] = (v2f){t.z, t.w}; }
;                 }
; #pragma unroll
;                 for (int bj = 0; bj < 2; ++bj) {
;                     float v[8];
; #pragma unroll
;                     for (int i = 0; i < 4; ++i) { v[i] = acc[ai][bj][m][0][i]; v[4 + i] = acc[ai][bj][m][1][i]; }
;                     const int col = pn * 256 + bj * 128 + tc0;
;                     if constexpr (MODE <= 1) {
;                         if ((wc & 1) == 0) {
;                             const float sgn = fq == 0 ? -1.f : 1.f;
; #pragma unroll
;                             for (int i = 0; i < 8; ++i) { const float pr = __shfl_xor(v[i], 16); const float r = v[i] * cs[i].x + sgn * pr * cs[i].y; v[i] = fq < 2 ? r : v[i]; }
;                         }
.LBB0_507:
	s_or_b64 exec, exec, s[2:3]
	v_or_b32_e32 v177, 48, v180
	v_bitop3_b32 v130, v180, s73, 48 bitop3:0xc8
	v_cmp_gt_i32_e64 s[8:9], s67, v177
	v_cmp_lt_i32_e64 s[6:7], s75, v177
	s_and_b64 vcc, exec, s[4:5]
	v_cndmask_b32_e64 v130, v200, v130, s[8:9]
	v_lshlrev_b32_e32 v130, 6, v130
	s_mov_b64 s[2:3], -1
	s_cbranch_vccnz .LBB0_509
	v_mov_b64_e32 v[136:137], v[16:17]
	s_mov_b64 s[2:3], 0
	v_mov_b32_e32 v184, v17
	v_mov_b32_e32 v179, v16
	v_mov_b32_e32 v186, v15
	v_mov_b32_e32 v185, v14
	v_mov_b32_e32 v219, v13
	v_mov_b32_e32 v187, v12
	v_mov_b32_e32 v221, v11
	v_mov_b32_e32 v220, v10
	v_mov_b64_e32 v[134:135], v[14:15]
	v_mov_b64_e32 v[132:133], v[12:13]
	v_mov_b64_e32 v[130:131], v[10:11]
.LBB0_509:
	s_andn2_b64 vcc, exec, s[2:3]
	s_cbranch_vccnz .LBB0_511
	v_and_b32_e32 v131, 64, v216
	v_xor_b32_e32 v130, 16, v216
	v_add_u32_e32 v131, 64, v131
	v_cmp_lt_i32_e32 vcc, v130, v131
	s_waitcnt vmcnt(4)
	v_mov_b32_e32 v131, v241
	v_mov_b32_e32 v135, v243
	v_cndmask_b32_e32 v130, v216, v130, vcc
	v_lshlrev_b32_e32 v179, 2, v130
	ds_bpermute_b32 v132, v179, v10
	ds_bpermute_b32 v134, v179, v11
	ds_bpermute_b32 v136, v179, v12
	v_mov_b32_e32 v130, v10
	ds_bpermute_b32 v181, v179, v14
	s_waitcnt lgkmcnt(3)
	v_cndmask_b32_e64 v133, v132, -v132, s[0:1]
	v_mov_b32_e32 v132, v240
	v_pk_mul_f32 v[130:131], v[130:131], v[132:133]
	s_waitcnt lgkmcnt(2)
	v_cndmask_b32_e64 v133, v134, -v134, s[0:1]
	v_mov_b32_e32 v134, v11
	v_mov_b32_e32 v132, v242
	v_pk_mul_f32 v[132:133], v[134:135], v[132:133]
	v_add_f32_e32 v130, v130, v131
	v_add_f32_e32 v131, v132, v133
	s_waitcnt lgkmcnt(1)
	v_cndmask_b32_e64 v133, v136, -v136, s[0:1]
	ds_bpermute_b32 v136, v179, v13
	v_mov_b32_e32 v134, v12
	v_mov_b32_e32 v135, v237
	v_mov_b32_e32 v132, v236
	v_pk_mul_f32 v[132:133], v[134:135], v[132:133]
	s_waitcnt lgkmcnt(0)
	v_cndmask_b32_e64 v135, v136, -v136, s[0:1]
	v_mov_b32_e32 v136, v13
	v_mov_b32_e32 v137, v239
	v_mov_b32_e32 v134, v238
	v_pk_mul_f32 v[134:135], v[136:137], v[134:135]
	v_add_f32_e32 v132, v132, v133
	v_add_f32_e32 v133, v134, v135
	v_cndmask_b32_e64 v135, v181, -v181, s[0:1]
	ds_bpermute_b32 v181, v179, v15
	v_mov_b32_e32 v136, v14
	v_mov_b32_e32 v137, v233
	v_mov_b32_e32 v134, v232
	v_pk_mul_f32 v[134:135], v[136:137], v[134:135]
	s_waitcnt lgkmcnt(0)
	v_cndmask_b32_e64 v137, v181, -v181, s[0:1]
	ds_bpermute_b32 v181, v179, v16
	ds_bpermute_b32 v179, v179, v17
	v_mov_b32_e32 v182, v15
	v_mov_b32_e32 v183, v235
	v_mov_b32_e32 v136, v234
	v_pk_mul_f32 v[136:137], v[182:183], v[136:137]
	v_add_f32_e32 v134, v134, v135
	v_add_f32_e32 v135, v136, v137
	s_waitcnt lgkmcnt(1)
	v_cndmask_b32_e64 v137, v181, -v181, s[0:1]
	v_mov_b32_e32 v182, v16
	v_mov_b32_e32 v183, v229
	v_mov_b32_e32 v136, v228
	v_pk_mul_f32 v[136:137], v[182:183], v[136:137]
	s_waitcnt lgkmcnt(0)
	v_cndmask_b32_e64 v183, v179, -v179, s[0:1]
	v_mov_b32_e32 v184, v17
	v_mov_b32_e32 v185, v231
	v_mov_b32_e32 v182, v230
	v_pk_mul_f32 v[182:183], v[184:185], v[182:183]
	v_add_f32_e32 v136, v136, v137
	v_add_f32_e32 v137, v182, v183
	v_cndmask_b32_e64 v130, v10, v130, s[10:11]
	v_cndmask_b32_e64 v131, v11, v131, s[10:11]
	v_cndmask_b32_e64 v132, v12, v132, s[10:11]
	v_cndmask_b32_e64 v133, v13, v133, s[10:11]
	v_cndmask_b32_e64 v134, v14, v134, s[10:11]
	v_cndmask_b32_e64 v135, v15, v135, s[10:11]
	v_cndmask_b32_e64 v136, v16, v136, s[10:11]
	v_cndmask_b32_e64 v137, v17, v137, s[10:11]
	v_mov_b32_e32 v220, v130
	v_mov_b32_e32 v221, v131
	v_mov_b32_e32 v187, v132
	v_mov_b32_e32 v219, v133
	v_mov_b32_e32 v185, v134
	v_mov_b32_e32 v186, v135
	v_mov_b32_e32 v179, v136
	v_mov_b32_e32 v184, v137

; DI void st8f_nt(float* p, const float (&v)[8]) { __builtin_nontemporal_store((v4f){v[0], v[1], v[2], v[3]}, (v4f*)p); __builtin_nontemporal_store((v4f){v[4], v[5], v[6], v[7]}, (v4f*)(p + 4)); }
;     template <int MODE>
;     DI void rows(const pg8::f32x4 (&acc)[2][2][4][2], const pg8::Unit& u, int wr, int wc, int fr, int fq) const {
;     ...
;                     const int col = pn * 256 + bj * 128 + tc0;
;                     if constexpr (MODE <= 1) {
;                         if ((wc & 1) == 0) {
;                             const float sgn = fq == 0 ? -1.f : 1.f;
; #pragma unroll
;                             for (int i = 0; i < 8; ++i) { const float pr = __shfl_xor(v[i], 16); const float r = v[i] * cs[i].x + sgn * pr * cs[i].y; v[i] = fq < 2 ? r : v[i]; }
;                         }
;                         if constexpr (MODE == 0) {
; #pragma unroll
;                             for (int i = 0; i < 8; ++i) v[i] *= QA_SCALE;
;                         }
;                     }
;                     if constexpr (MODE == 1 || MODE == 2) {
;                         const int cs1 = (pn & 3) * 256 + bj * 128 + tc0;
;                         float* dst = row < MP ? out + (MODE == 1 ? O_KP : O_VP) + (size_t)row * 1024 + cs1 : out + (MODE == 1 ? O_KS : O_VS) + (size_t)(row - MP) * 1024 + cs1;
;                         st8f_nt(dst, v);
;     ...
;                     } else if constexpr (MODE == 1 || MODE == 2) {
;                         if (row < MP) {
;                             const int cc = (pn & 3) * 256 + bj * 128 + tc0, hd = cc >> 7;
;                             st8bf((MODE == 1 ? KC : VC) + ((size_t)((row >> 12) * 8 + hd) * SEQ + (row & (SEQ - 1))) * 128 + (cc & 127), v);
;                         } else st8bf(P + (size_t)row * PLD + col, v);
.LBB0_518:
	v_and_b32_e32 v131, 64, v216
	v_xor_b32_e32 v130, 16, v216
	v_add_u32_e32 v131, 64, v131
	v_cmp_lt_i32_e32 vcc, v130, v131
	s_waitcnt vmcnt(2)
	v_mov_b32_e32 v131, v241
	v_mov_b32_e32 v133, v243
	v_cndmask_b32_e32 v130, v216, v130, vcc
	v_lshlrev_b32_e32 v177, 2, v130
	ds_bpermute_b32 v130, v177, v2
	v_mov_b32_e32 v135, v239
	v_mov_b32_e32 v137, v235
	s_waitcnt lgkmcnt(0)
	v_cndmask_b32_e64 v132, v130, -v130, s[0:1]
	v_mov_b32_e32 v130, v2
	v_mov_b32_e32 v241, v132
	v_pk_mul_f32 v[130:131], v[130:131], v[240:241]
	v_mov_b32_e32 v132, v3
	v_add_f32_e32 v130, v130, v131
	ds_bpermute_b32 v131, v177, v3
	v_cndmask_b32_e64 v130, v2, v130, s[10:11]
	v_mov_b32_e32 v221, v130
	s_waitcnt lgkmcnt(0)
	v_cndmask_b32_e64 v131, v131, -v131, s[0:1]
	v_mov_b32_e32 v243, v131
	v_pk_mul_f32 v[132:133], v[132:133], v[242:243]
	s_nop 0
	v_add_f32_e32 v131, v132, v133
	ds_bpermute_b32 v132, v177, v4
	v_mov_b32_e32 v133, v237
	v_cndmask_b32_e64 v131, v3, v131, s[10:11]
	v_mov_b32_e32 v222, v131
	s_waitcnt lgkmcnt(0)
	v_cndmask_b32_e64 v134, v132, -v132, s[0:1]
	v_mov_b32_e32 v132, v4
	v_mov_b32_e32 v237, v134
	v_pk_mul_f32 v[132:133], v[132:133], v[236:237]
	v_mov_b32_e32 v134, v5
	v_add_f32_e32 v132, v132, v133
	ds_bpermute_b32 v133, v177, v5
	v_cndmask_b32_e64 v132, v4, v132, s[10:11]
	v_mov_b32_e32 v219, v132
	s_waitcnt lgkmcnt(0)
	v_cndmask_b32_e64 v133, v133, -v133, s[0:1]
	v_mov_b32_e32 v239, v133
	v_pk_mul_f32 v[134:135], v[134:135], v[238:239]
	s_nop 0
	v_add_f32_e32 v133, v134, v135
	ds_bpermute_b32 v134, v177, v6
	v_mov_b32_e32 v135, v233
	v_cndmask_b32_e64 v133, v5, v133, s[10:11]
	v_mov_b32_e32 v220, v133
	s_waitcnt lgkmcnt(0)
	v_cndmask_b32_e64 v136, v134, -v134, s[0:1]
	v_mov_b32_e32 v134, v6
	v_mov_b32_e32 v233, v136
	v_pk_mul_f32 v[134:135], v[134:135], v[232:233]
	v_mov_b32_e32 v136, v7
	v_add_f32_e32 v134, v134, v135
	ds_bpermute_b32 v135, v177, v7
	v_cndmask_b32_e64 v134, v6, v134, s[10:11]
	v_mov_b32_e32 v186, v134
	s_waitcnt lgkmcnt(0)
	v_cndmask_b32_e64 v135, v135, -v135, s[0:1]
	v_mov_b32_e32 v235, v135
	v_pk_mul_f32 v[136:137], v[136:137], v[234:235]
	s_nop 0
	v_add_f32_e32 v135, v136, v137
	ds_bpermute_b32 v136, v177, v8
	v_mov_b32_e32 v137, v229
	v_cndmask_b32_e64 v135, v7, v135, s[10:11]
	v_mov_b32_e32 v187, v135
	s_waitcnt lgkmcnt(0)
	v_cndmask_b32_e64 v232, v136, -v136, s[0:1]
	v_mov_b32_e32 v136, v8
	v_mov_b32_e32 v229, v232
	v_pk_mul_f32 v[136:137], v[136:137], v[228:229]
	v_mov_b32_e32 v228, v9
	v_add_f32_e32 v136, v136, v137
	ds_bpermute_b32 v137, v177, v9
	v_mov_b32_e32 v229, v231
	v_cndmask_b32_e64 v136, v8, v136, s[10:11]
	v_mov_b32_e32 v184, v136
	s_waitcnt lgkmcnt(0)
	v_cndmask_b32_e64 v137, v137, -v137, s[0:1]
	v_mov_b32_e32 v231, v137
	v_pk_mul_f32 v[228:229], v[228:229], v[230:231]
	s_nop 0
	v_add_f32_e32 v137, v228, v229
	v_cndmask_b32_e64 v137, v9, v137, s[10:11]
	v_mov_b32_e32 v185, v137
.LBB0_519:
	v_mov_b32_e32 v179, v163
	s_waitcnt vmcnt(5)
	v_lshl_add_u64 v[228:229], v[182:183], 0, v[178:179]
	global_store_dwordx4 v[228:229], v[130:133], off offset:512 nt
	global_store_dwordx4 v[228:229], v[134:137], off offset:528 nt
	s_and_saveexec_b64 s[2:3], s[6:7]
	s_xor_b64 s[2:3], exec, s[2:3]
	s_cbranch_execz .LBB0_521
	v_lshl_add_u64 v[134:135], v[174:175], 1, v[180:181]
	v_cvt_pk_bf16_f32 v130, v221, v222
	v_cvt_pk_bf16_f32 v131, v219, v220
	v_cvt_pk_bf16_f32 v132, v186, v187
	v_cvt_pk_bf16_f32 v133, v184, v185
	global_store_dwordx4 v[134:135], v[130:133], off offset:256
